# speedup vs baseline: 1.0299x; 1.0117x over previous
.LBB0_601:
	s_or_b64 exec, exec, s[0:1]
	v_mov_b32_e32 v220, v218
	s_cmpk_lt_i32 s70, 0x200
	s_waitcnt lgkmcnt(0)
	s_barrier
	s_cselect_b64 s[10:11], -1, 0
	s_cmpk_gt_i32 s70, 0x1ff
	v_readfirstlane_b32 s12, v220
	s_cbranch_scc1 .LBB0_604
	s_and_b32 s99, s70, 1
	s_lshl_b32 s99, s99, 8
	s_add_i32 s99, s99, s70
	s_ashr_i32 s0, s99, 31
	s_lshr_b32 s0, s0, 29
	s_add_i32 s2, s99, s0
	s_and_b32 s0, s2, -8
	s_sub_i32 s3, s99, s0
	s_cmp_gt_i32 s3, -1
	s_cbranch_scc0 .LBB0_605
	s_lshl_b32 s4, s3, 6
	s_cbranch_execz .LBB0_606
	s_branch .LBB0_607

.LBB0_613:
	s_add_i32 s50, s50, 1
	s_and_b32 s98, s70, 1
	s_add_i32 s98, s98, s50
	s_and_b32 s98, s98, 1
	s_mul_i32 s10, s98, s62
	s_add_i32 s10, s10, s70
	s_cmpk_lt_i32 s50, 2
	s_cselect_b64 s[34:35], -1, 0
	s_cmpk_gt_i32 s50, 1
	s_cbranch_scc1 .LBB0_619
	s_ashr_i32 s5, s10, 31
	s_lshr_b32 s5, s5, 29
	s_add_i32 s5, s10, s5
	s_and_b32 s11, s5, -8
	s_sub_i32 s12, s10, s11
	s_cmp_gt_i32 s12, -1
	s_mov_b64 s[10:11], -1
	s_cbranch_scc0 .LBB0_616
	s_lshl_b32 s13, s12, 6
	s_mov_b64 s[10:11], 0

.LBB0_894:
	s_or_b64 exec, exec, s[0:1]
	v_mov_b32_e32 v182, v218
	s_waitcnt lgkmcnt(0)
	s_barrier
	s_and_b64 vcc, exec, s[8:9]
	v_readfirstlane_b32 s16, v182
	s_cbranch_vccnz .LBB0_897
	s_and_b32 s99, s70, 1
	s_lshl_b32 s99, s99, 8
	s_add_i32 s99, s99, s70
	s_ashr_i32 s0, s99, 31
	s_lshr_b32 s0, s0, 29
	s_add_i32 s2, s99, s0
	s_and_b32 s0, s2, -8
	s_sub_i32 s3, s99, s0
	s_cmp_gt_i32 s3, -1
	s_cbranch_scc0 .LBB0_898
	s_lshl_b32 s4, s3, 6
	s_cbranch_execz .LBB0_899
	s_branch .LBB0_900

.LBB0_906:
	s_add_i32 s35, s35, 1
	s_and_b32 s98, s70, 1
	s_add_i32 s98, s98, s35
	s_and_b32 s98, s98, 1
	s_mul_i32 s21, s98, s62
	s_add_i32 s21, s21, s70
	s_cmpk_lt_i32 s35, 2
	s_cselect_b64 s[18:19], -1, 0
	s_cmpk_gt_i32 s35, 1
	s_cbranch_scc1 .LBB0_912
	s_ashr_i32 s1, s21, 31
	s_lshr_b32 s1, s1, 29
	s_add_i32 s1, s21, s1
	s_and_b32 s20, s1, -8
	s_sub_i32 s22, s21, s20
	s_cmp_gt_i32 s22, -1
	s_mov_b64 s[20:21], -1
	s_cbranch_scc0 .LBB0_909
	s_lshl_b32 s23, s22, 6
	s_mov_b64 s[20:21], 0

.LBB0_1064:
	s_or_b64 exec, exec, s[0:1]
	v_mov_b32_e32 v154, v218
	s_waitcnt lgkmcnt(0)
	s_barrier
	s_and_b64 vcc, exec, s[8:9]
	v_readfirstlane_b32 s7, v154
	s_cbranch_vccnz .LBB0_1088
	s_and_b32 s99, s70, 1
	s_lshl_b32 s99, s99, 8
	s_add_i32 s99, s99, s70
	s_ashr_i32 s0, s99, 31
	s_lshr_b32 s0, s0, 29
	s_add_i32 s4, s99, s0
	s_and_b32 s0, s4, -8
	s_sub_i32 s2, s99, s0
	s_cmp_gt_i32 s2, -1
	s_cbranch_scc0 .LBB0_1067
	s_lshl_b32 s3, s2, 6
	s_ashr_i32 s0, s4, 3
	s_cbranch_execz .LBB0_1068
	s_branch .LBB0_1069

.LBB0_1074:
	s_add_i32 s37, s37, 1
	s_and_b32 s98, s70, 1
	s_add_i32 s98, s98, s37
	s_and_b32 s98, s98, 1
	s_mul_i32 s21, s98, s62
	s_add_i32 s21, s21, s70
	s_cmpk_lt_i32 s37, 2
	s_cselect_b64 s[18:19], -1, 0
	s_cmpk_gt_i32 s37, 1
	s_cbranch_scc1 .LBB0_1080
	s_ashr_i32 s20, s21, 31
	s_lshr_b32 s20, s20, 29
	s_add_i32 s22, s21, s20
	s_and_b32 s20, s22, -8
	s_sub_i32 s23, s21, s20
	s_cmp_gt_i32 s23, -1
	s_mov_b64 s[20:21], -1
	s_cbranch_scc0 .LBB0_1077
	s_lshl_b32 s24, s23, 6
	s_mov_b64 s[20:21], 0
